# v24 + nt hint on P0's once-read f32 x rows and w_in tiles
# speedup vs baseline: 1.0779x; 1.0153x over previous
; #define GAS __attribute__((address_space(1)))
; __device__ __forceinline__ void rms9_issue(const float* x0_, const float* xe, f32x4 (&v)[9][4], int lane) {
; #pragma unroll
;     for (int r = 0; r < 8; ++r)
; #pragma unroll
;         for (int j = 0; j < 4; ++j) v[r][j] = ((const GAS f32x4*)(x0_ + (size_t)r * DM))[lane + 64 * j];
; #pragma unroll
;     for (int j = 0; j < 4; ++j) v[8][j] = xe ? ((const GAS f32x4*)xe)[lane + 64 * j] : (f32x4){0.f, 0.f, 0.f, 0.f};
; }
; __device__ __forceinline__ void s5_tables_fetch(Frame& F, int item, S5TabRegs& R) {
;     const int tid = F.tid, g = item >> 3; const int n0 = tid & 63;
;     R.a_re = F.in[8][g * S5N + n0]; R.a_im = F.in[9][g * S5N + n0]; R.dtl = F.in[10][g];
; #pragma unroll
;     for (int i = 0; i < 2; ++i) { const int idx = tid + 512 * i;
;         { const int c = idx >> 6, n = idx & 63; R.cr[i] = F.in[13][(size_t)(g * 16 + c) * S5N + n]; R.ci[i] = F.in[14][(size_t)(g * 16 + c) * S5N + n]; }
;         { const int n = idx >> 4, c = idx & 15; R.br[i] = F.in[11][(size_t)(g * S5N + n) * 16 + c]; R.bi[i] = F.in[12][(size_t)(g * S5N + n) * 16 + c]; } }
.LBB0_5:
	s_or_b64 exec, exec, s[4:5]
	s_load_dwordx2 s[6:7], s[0:1], 0xd0
	s_lshr_b32 s96, s20, 6
	s_lshl_b32 s3, s2, 3
	s_add_i32 s34, s3, s96
	s_lshl_b32 s18, s52, 3
	s_add_u32 s46, s50, 0x1b00000
	s_addc_u32 s47, s51, 0
	s_waitcnt lgkmcnt(0)
	s_cmp_lt_i32 s6, 1
	s_cselect_b64 s[4:5], -1, 0
	s_cmp_gt_i32 s7, 0
	s_cselect_b64 s[6:7], -1, 0
	s_and_b64 s[72:73], s[4:5], s[6:7]
	s_andn2_b64 vcc, exec, s[72:73]
	v_and_b32_e32 v154, 63, v0
	v_writelane_b32 v238, s20, 25
	s_cbranch_vccnz .LBB0_71
	s_cmpk_lg_i32 s52, 0x100
	s_cselect_b64 s[12:13], -1, 0
	s_mov_b64 s[4:5], -1
	s_and_b64 vcc, exec, s[12:13]
	v_or_b32_e32 v150, 64, v154
	s_cbranch_vccnz .LBB0_43
	s_ashr_i32 s4, s2, 3
	s_lshl_b32 s3, s4, 6
	v_or_b32_e32 v2, s3, v154
	v_ashrrev_i32_e32 v3, 31, v2
	s_ashr_i32 s5, s4, 31
	v_lshlrev_b64 v[2:3], 2, v[2:3]
	s_lshl_b64 s[6:7], s[4:5], 2
	v_lshl_add_u64 v[4:5], s[80:81], 0, v[2:3]
	v_lshl_add_u64 v[2:3], s[82:83], 0, v[2:3]
	s_add_u32 s6, s84, s6
	global_load_dword v165, v[2:3], off
	s_addc_u32 s7, s85, s7
	s_lshl_b32 s5, s4, 4
	v_lshrrev_b32_e32 v3, 6, v0
	global_load_dword v164, v[4:5], off
	v_or_b32_e32 v4, s5, v3
	v_ashrrev_i32_e32 v5, 31, v4
	v_lshlrev_b64 v[4:5], 8, v[4:5]
	v_lshlrev_b32_e32 v146, 2, v154
	v_or_b32_e32 v4, v4, v146
	v_lshl_add_u64 v[6:7], s[90:91], 0, v[4:5]
	v_lshl_add_u64 v[4:5], s[92:93], 0, v[4:5]
	v_lshrrev_b32_e32 v158, 4, v0
	global_load_dword v149, v[4:5], off
	v_or_b32_e32 v4, s3, v158
	v_and_b32_e32 v1, 15, v0
	v_ashrrev_i32_e32 v5, 31, v4
	v_lshlrev_b64 v[4:5], 6, v[4:5]
	v_lshlrev_b32_e32 v147, 2, v1
	s_load_dwordx16 s[56:71], s[0:1], 0x0
	v_or_b32_e32 v4, v4, v147
	v_or_b32_e32 v148, 0x200, v0
	global_load_dword v153, v[6:7], off
	v_lshl_add_u64 v[6:7], s[86:87], 0, v[4:5]
	v_lshl_add_u64 v[4:5], s[88:89], 0, v[4:5]
	v_lshrrev_b32_e32 v3, 6, v148
	s_lshl_b32 s22, s34, 3
	v_mov_b32_e32 v2, 0
	global_load_dword v157, v[4:5], off
	v_or_b32_e32 v4, s5, v3
	s_ashr_i32 s23, s22, 31
	global_load_dword v166, v2, s[6:7]
	v_ashrrev_i32_e32 v5, 31, v4
	s_lshl_b64 s[6:7], s[22:23], 12
	v_lshlrev_b64 v[4:5], 8, v[4:5]
	s_waitcnt lgkmcnt(0)
	s_add_u32 s8, s56, s6
	v_or_b32_e32 v4, v4, v146
	s_addc_u32 s9, s57, s7
	s_ashr_i32 s35, s34, 31
	global_load_dword v156, v[6:7], off
	v_lshl_add_u64 v[6:7], s[90:91], 0, v[4:5]
	v_lshl_add_u64 v[4:5], s[92:93], 0, v[4:5]
	v_lshrrev_b32_e32 v161, 4, v148
	s_lshl_b64 s[6:7], s[34:35], 12
	global_load_dword v159, v[4:5], off
	v_or_b32_e32 v4, s3, v161
	s_add_u32 s3, s58, s6
	s_addc_u32 s5, s59, s7
	s_cmpk_lt_i32 s34, 0x400
	s_cselect_b64 s[20:21], -1, 0
	s_and_b64 s[6:7], s[20:21], exec
	s_cselect_b32 s7, s5, 0
	s_cselect_b32 s6, s3, 0
	s_add_u32 s10, s8, 0x1000
	s_addc_u32 s11, s9, 0
	s_add_u32 s14, s8, 0x2000
	s_addc_u32 s15, s9, 0
	s_add_u32 s16, s8, 0x3000
	s_addc_u32 s17, s9, 0
	s_add_u32 s24, s8, 0x4000
	s_addc_u32 s25, s9, 0
	s_add_u32 s26, s8, 0x5000
	v_ashrrev_i32_e32 v5, 31, v4
	s_addc_u32 s27, s9, 0
	v_lshlrev_b64 v[4:5], 6, v[4:5]
	s_add_u32 s28, s8, 0x6000
	v_or_b32_e32 v4, v4, v147
	s_addc_u32 s29, s9, 0
	global_load_dword v160, v[6:7], off
	v_lshl_add_u64 v[6:7], s[86:87], 0, v[4:5]
	v_lshl_add_u64 v[4:5], s[88:89], 0, v[4:5]
	v_or_b32_e32 v155, 0x80, v154
	v_or_b32_e32 v151, 0xc0, v154
	v_lshlrev_b32_e32 v3, 4, v150
	s_add_u32 s30, s8, 0x7000
	global_load_dword v162, v[6:7], off
	global_load_dword v163, v[4:5], off
	v_lshlrev_b32_e32 v152, 4, v154
	v_lshlrev_b32_e32 v4, 4, v155
	v_lshlrev_b32_e32 v5, 4, v151
	global_load_dwordx4 v[90:93], v3, s[10:11] nt
	global_load_dwordx4 v[82:85], v3, s[14:15] nt
	global_load_dwordx4 v[86:89], v3, s[16:17] nt
	global_load_dwordx4 v[78:81], v3, s[24:25] nt
	s_addc_u32 s31, s9, 0
	global_load_dwordx4 v[102:105], v3, s[26:27] nt
	global_load_dwordx4 v[98:101], v3, s[28:29] nt
	global_load_dwordx4 v[94:97], v3, s[30:31] nt
	global_load_dwordx4 v[66:69], v4, s[10:11] nt
	global_load_dwordx4 v[62:65], v4, s[14:15] nt
	global_load_dwordx4 v[58:61], v4, s[16:17] nt
	global_load_dwordx4 v[54:57], v4, s[24:25] nt
	global_load_dwordx4 v[50:53], v4, s[26:27] nt
	global_load_dwordx4 v[46:49], v4, s[28:29] nt
	global_load_dwordx4 v[42:45], v4, s[30:31] nt
	global_load_dwordx4 v[34:37], v5, s[10:11] nt
	global_load_dwordx4 v[30:33], v5, s[14:15] nt
	global_load_dwordx4 v[26:29], v5, s[16:17] nt
	global_load_dwordx4 v[22:25], v5, s[24:25] nt
	global_load_dwordx4 v[18:21], v5, s[26:27] nt
	global_load_dwordx4 v[14:17], v5, s[28:29] nt
	global_load_dwordx4 v[6:9], v5, s[30:31] nt
	global_load_dwordx4 v[142:145], v152, s[8:9] nt
	global_load_dwordx4 v[106:109], v152, s[8:9] offset:1024 nt
	global_load_dwordx4 v[70:73], v152, s[8:9] offset:2048 nt
	global_load_dwordx4 v[38:41], v152, s[8:9] offset:3072 nt
	global_load_dwordx4 v[138:141], v152, s[10:11] nt
	global_load_dwordx4 v[134:137], v152, s[14:15] nt
	global_load_dwordx4 v[130:133], v152, s[16:17] nt
	global_load_dwordx4 v[126:129], v152, s[24:25] nt
	global_load_dwordx4 v[122:125], v152, s[26:27] nt
	global_load_dwordx4 v[118:121], v152, s[28:29] nt
	global_load_dwordx4 v[114:117], v152, s[30:31] nt
	s_cmp_lg_u64 s[6:7], 0
	s_cselect_b64 s[8:9], -1, 0
	s_cmp_eq_u64 s[6:7], 0
	v_mov_b32_e32 v110, 0
	v_mov_b32_e32 v111, 0
	v_mov_b32_e32 v112, 0
	v_mov_b32_e32 v113, 0
	v_mov_b32_e32 v74, 0
	v_mov_b32_e32 v75, 0
	v_mov_b32_e32 v76, 0
	v_mov_b32_e32 v77, 0
	s_cbranch_scc1 .LBB0_9
	global_load_dwordx4 v[110:113], v152, s[6:7] nt
	global_load_dwordx4 v[74:77], v152, s[6:7] offset:1024 nt
.LBB0_9:
	s_andn2_b64 vcc, exec, s[8:9]
	v_mov_b32_e32 v3, 0
	v_mov_b32_e32 v4, 0
	v_mov_b32_e32 v5, 0
	v_mov_b32_e32 v10, 0
	v_mov_b32_e32 v11, 0
	v_mov_b32_e32 v12, 0
	v_mov_b32_e32 v13, 0
	s_cbranch_vccnz .LBB0_11
	global_load_dwordx4 v[2:5], v152, s[6:7] offset:2048 nt
	global_load_dwordx4 v[10:13], v152, s[6:7] offset:3072 nt

; #define LAS __attribute__((address_space(3)))
; __device__ __forceinline__ void transpose_issue_lds(const float* W, int ldw, int k0, int sn0, int lane, LAS unsigned char* IMG) {
; #pragma unroll
;     for (int i = 0; i < 16; ++i)
;         __builtin_amdgcn_global_load_lds((const unsigned*)(W + (size_t)(k0 + 4 * i + (lane >> 4)) * ldw + sn0 + 4 * (lane & 15)), (LAS unsigned*)(IMG + i * 1024), 16, 0, 0);
; }
; __device__ __forceinline__ void p0_prologue(Frame& F) {
;     ...
;         const int wr_ = F.bid + 256 * F.wave; const bool hasw = wr_ < I_IN;
;         const int nblk_ = INC / 64, kb_ = wr_ / nblk_, sn0_ = (wr_ % nblk_) * 64, seg_ = sn0_ / 512;
;         const int dseg_ = seg_ == 0 ? 0 : seg_ == 1 ? 1 : seg_ == 2 ? 4 : seg_ == 3 ? 2 : 3;
;         LAS unsigned char* IMG = F.lds + 98304 + (F.wave < 3 ? F.wave : 0) * 16384;
;         if (hasw) transpose_issue_lds(F.in[7], INC, kb_ * 64, sn0_, F.lane, IMG);
.LBB0_13:
	s_cmpk_lt_i32 s5, 0x280
	s_cselect_b64 s[16:17], -1, 0
	s_lshl_b32 s14, s6, 6
	s_lshl_b32 s6, s96, 14
	v_readlane_b32 s7, v238, 25
	s_cmpk_lt_u32 s7, 0xc0
	s_cselect_b32 s6, s6, 0
	s_add_i32 s31, s6, 0
	s_add_i32 s31, s31, 0x18000
	s_cmpk_gt_i32 s5, 0x27f
	s_cbranch_scc1 .LBB0_15
	s_load_dwordx16 s[56:71], s[0:1], 0x0
	s_ashr_i32 s15, s14, 31
	s_lshl_b64 s[6:7], s[14:15], 2
	v_lshlrev_b32_e32 v168, 4, v0
	v_lshrrev_b32_e32 v167, 4, v154
	s_waitcnt lgkmcnt(0)
	s_add_u32 s6, s70, s6
	s_addc_u32 s7, s71, s7
	v_and_b32_e32 v168, 0xf0, v168
	v_mov_b32_e32 v169, 0
	v_lshl_or_b32 v167, s30, 6, v167
	v_lshl_add_u64 v[168:169], s[6:7], 0, v[168:169]
	s_movk_i32 s5, 0x2800
	s_mov_b32 m0, s31
	v_mad_i64_i32 v[170:171], s[6:7], v167, s5, v[168:169]
	global_load_lds_dwordx4 v[170:171], off nt
	v_or_b32_e32 v170, 4, v167
	v_mad_i64_i32 v[170:171], s[6:7], v170, s5, v[168:169]
	s_add_i32 m0, s31, 0x400
	s_nop 0
	global_load_lds_dwordx4 v[170:171], off nt
	v_or_b32_e32 v170, 8, v167
	v_mad_i64_i32 v[170:171], s[6:7], v170, s5, v[168:169]
	s_add_i32 m0, s31, 0x800
	s_nop 0
	global_load_lds_dwordx4 v[170:171], off nt
	v_or_b32_e32 v170, 12, v167
	v_mad_i64_i32 v[170:171], s[6:7], v170, s5, v[168:169]
	s_add_i32 m0, s31, 0xc00
	s_nop 0
	global_load_lds_dwordx4 v[170:171], off nt
	v_or_b32_e32 v170, 16, v167
	v_mad_i64_i32 v[170:171], s[6:7], v170, s5, v[168:169]
	s_add_i32 m0, s31, 0x1000
	s_nop 0
	global_load_lds_dwordx4 v[170:171], off nt
	v_or_b32_e32 v170, 20, v167
	v_mad_i64_i32 v[170:171], s[6:7], v170, s5, v[168:169]
	s_add_i32 m0, s31, 0x1400
	s_nop 0
	global_load_lds_dwordx4 v[170:171], off nt
	v_or_b32_e32 v170, 24, v167
	v_mad_i64_i32 v[170:171], s[6:7], v170, s5, v[168:169]
	s_add_i32 m0, s31, 0x1800
	s_nop 0
	global_load_lds_dwordx4 v[170:171], off nt
	v_or_b32_e32 v170, 28, v167
	v_mad_i64_i32 v[170:171], s[6:7], v170, s5, v[168:169]
	s_add_i32 m0, s31, 0x1c00
	s_nop 0
	global_load_lds_dwordx4 v[170:171], off nt
	v_or_b32_e32 v170, 32, v167
	v_mad_i64_i32 v[170:171], s[6:7], v170, s5, v[168:169]
	s_add_i32 m0, s31, 0x2000
	s_nop 0
	global_load_lds_dwordx4 v[170:171], off nt
	v_or_b32_e32 v170, 36, v167
	v_mad_i64_i32 v[170:171], s[6:7], v170, s5, v[168:169]
	s_add_i32 m0, s31, 0x2400
	s_nop 0
	global_load_lds_dwordx4 v[170:171], off nt
	v_or_b32_e32 v170, 40, v167
	v_mad_i64_i32 v[170:171], s[6:7], v170, s5, v[168:169]
	s_add_i32 m0, s31, 0x2800
	s_nop 0
	global_load_lds_dwordx4 v[170:171], off nt
	v_or_b32_e32 v170, 44, v167
	v_mad_i64_i32 v[170:171], s[6:7], v170, s5, v[168:169]
	s_add_i32 m0, s31, 0x2c00
	s_nop 0
	global_load_lds_dwordx4 v[170:171], off nt
	v_or_b32_e32 v170, 48, v167
	v_mad_i64_i32 v[170:171], s[6:7], v170, s5, v[168:169]
	s_add_i32 m0, s31, 0x3000
	s_nop 0
	global_load_lds_dwordx4 v[170:171], off nt
	v_or_b32_e32 v170, 52, v167
	v_mad_i64_i32 v[170:171], s[6:7], v170, s5, v[168:169]
	s_add_i32 m0, s31, 0x3400
	s_nop 0
	global_load_lds_dwordx4 v[170:171], off nt
	v_or_b32_e32 v170, 56, v167
	v_mad_i64_i32 v[170:171], s[6:7], v170, s5, v[168:169]
	s_add_i32 m0, s31, 0x3800
	v_or_b32_e32 v167, 60, v167
	global_load_lds_dwordx4 v[170:171], off nt
	v_mad_i64_i32 v[168:169], s[6:7], v167, s5, v[168:169]
	s_add_i32 m0, s31, 0x3c00
	s_nop 0
	global_load_lds_dwordx4 v[168:169], off nt
